# memory cross-attention through LDS: fragment registers recycled in place (fragment k of the next tile pair is read as soon as the MFMAs of fragment k are issued), one barrier per pair
# baseline (speedup 1.0000x reference)
; __device__ __forceinline__ f32x4 mfma16(bf16x8 a, bf16x8 b, f32x4 c) { return __builtin_amdgcn_mfma_f32_16x16x32_bf16(a, b, c, 0, 0, 0); }
; __device__ __forceinline__ void mem_task(bf16_t* zb, const bf16_t* kvm_b, const bf16_t* vmt_b, int hm, int t0, int lane, bool do_store) {
;     const int n = lane & 15, fq = lane >> 4;
;     bf16_t* qp = zb + (size_t)(t0 + n) * ZM + ZC_QM + hm * 256;
;     bf16x8 qf[8];
; #pragma unroll
;     for (int kk = 0; kk < 8; ++kk) qf[kk] = *(const bf16x8*)(qp + kk * 32 + 8 * fq);
;     f32x4 zero4 = {0.f, 0.f, 0.f, 0.f}; asm volatile("" : "+v"(zero4));
;     f32x4 s[16];
;     const bf16_t* kbase = kvm_b + (size_t)(8 * (n >> 2) + (n & 3)) * 2048 + hm * 256 + 8 * fq;
;     bf16x8 kfr[3][8];
; #pragma unroll
;     for (int kk = 0; kk < 8; ++kk) kfr[0][kk] = *(const bf16x8*)(kbase + kk * 32);
;     { const bf16_t* kp = kbase + (size_t)4 * 2048;
; #pragma unroll
;       for (int kk = 0; kk < 8; ++kk) kfr[1][kk] = *(const bf16x8*)(kp + kk * 32); }
; #pragma unroll
;     for (int kt = 0; kt < 16; ++kt) {
;         if (kt + 2 < 16) { const bf16_t* kp = kbase + (size_t)(((kt + 2) >> 1) * 32 + 4 * ((kt + 2) & 1)) * 2048;
; #pragma unroll
;             for (int kk = 0; kk < 8; ++kk) kfr[(kt + 2) % 3][kk] = *(const bf16x8*)(kp + kk * 32); }
;         f32x4 acc = zero4;
;         __builtin_amdgcn_s_setprio(1);
; #pragma unroll
;         for (int kk = 0; kk < 8; ++kk) acc = mfma16(kfr[kt % 3][kk], qf[kk], acc);
;         __builtin_amdgcn_s_setprio(0);
;         s[kt] = acc; }
.LBB0_366:
	v_and_or_b32 v186, s0, -16, v65
	v_mov_b64_e32 v[188:189], s[78:79]
	s_and_b32 s2, s3, 0x300
	v_mad_i64_i32 v[188:189], s[6:7], v186, s11, v[188:189]
	s_lshl_b32 s38, s2, 1
	v_lshl_add_u64 v[188:189], v[188:189], 0, s[38:39]
	v_lshl_add_u64 v[184:185], v[188:189], 0, s[16:17]
	v_mov_b32_e32 v143, v64
	v_mov_b32_e32 v145, v64
	v_lshl_add_u64 v[188:189], v[184:185], 0, v[142:143]
	global_load_dwordx4 v[0:3], v[188:189], off
	global_load_dwordx4 v[4:7], v[188:189], off offset:64
	global_load_dwordx4 v[8:11], v[188:189], off offset:128
	global_load_dwordx4 v[12:15], v[188:189], off offset:192
	global_load_dwordx4 v[16:19], v[188:189], off offset:256
	global_load_dwordx4 v[20:23], v[188:189], off offset:320
	global_load_dwordx4 v[24:27], v[188:189], off offset:384
	global_load_dwordx4 v[28:31], v[188:189], off offset:448
	v_lshl_add_u64 v[184:185], v[184:185], 0, v[144:145]
	s_lshl_b32 s98, s2, 9
	s_mov_b32 s99, 0
	v_lshl_add_u64 v[180:181], v[66:67], 0, s[98:99]
	v_lshl_add_u64 v[182:183], v[140:141], 0, s[98:99]
	s_lshl_b32 s7, s89, 10
	s_sub_u32 s98, s7, 0x1000
	s_subb_u32 s99, 0, 0
	v_lshl_add_u64 v[180:181], v[180:181], 0, s[98:99]
	v_lshl_add_u64 v[182:183], v[182:183], 0, s[98:99]
	v_lshlrev_b32_e32 v178, 4, v204
	v_add_u32_e32 v179, 0x10000, v178
	s_mov_b64 s[98:99], 0x2000
	s_add_i32 m0, s7, 0
	s_nop 0
	global_load_lds_dwordx4 v[180:181], off
	v_lshl_add_u64 v[180:181], v[180:181], 0, s[98:99]
	s_add_i32 m0, s7, 8192
	s_nop 0
	global_load_lds_dwordx4 v[180:181], off
	v_lshl_add_u64 v[180:181], v[180:181], 0, s[98:99]
	s_add_i32 m0, s7, 16384
	s_nop 0
	global_load_lds_dwordx4 v[180:181], off
	v_lshl_add_u64 v[180:181], v[180:181], 0, s[98:99]
	s_add_i32 m0, s7, 24576
	s_nop 0
	global_load_lds_dwordx4 v[180:181], off
	v_lshl_add_u64 v[180:181], v[180:181], 0, s[98:99]
	s_add_i32 m0, s7, 32768
	s_nop 0
	global_load_lds_dwordx4 v[180:181], off
	v_lshl_add_u64 v[180:181], v[180:181], 0, s[98:99]
	s_add_i32 m0, s7, 40960
	s_nop 0
	global_load_lds_dwordx4 v[180:181], off
	v_lshl_add_u64 v[180:181], v[180:181], 0, s[98:99]
	s_add_i32 m0, s7, 49152
	s_nop 0
	global_load_lds_dwordx4 v[180:181], off
	v_lshl_add_u64 v[180:181], v[180:181], 0, s[98:99]
	s_add_i32 m0, s7, 57344
	s_nop 0
	global_load_lds_dwordx4 v[180:181], off
	v_lshl_add_u64 v[180:181], v[180:181], 0, s[98:99]
	s_add_i32 m0, s7, 65536
	s_nop 0
	global_load_lds_dwordx4 v[180:181], off
	v_lshl_add_u64 v[180:181], v[180:181], 0, s[98:99]
	s_add_i32 m0, s7, 73728
	s_nop 0
	global_load_lds_dwordx4 v[180:181], off
	v_lshl_add_u64 v[180:181], v[180:181], 0, s[98:99]
	s_add_i32 m0, s7, 81920
	s_nop 0
	global_load_lds_dwordx4 v[180:181], off
	v_lshl_add_u64 v[180:181], v[180:181], 0, s[98:99]
	s_add_i32 m0, s7, 90112
	s_nop 0
	global_load_lds_dwordx4 v[180:181], off
	v_lshl_add_u64 v[180:181], v[180:181], 0, s[98:99]
	s_waitcnt vmcnt(10)
	s_barrier
	ds_read_b128 v[104:107], v178 offset:0
	ds_read_b128 v[146:149], v178 offset:8192
	ds_read_b128 v[108:111], v178 offset:1024
	ds_read_b128 v[150:153], v178 offset:9216
	ds_read_b128 v[112:115], v178 offset:2048
	ds_read_b128 v[154:157], v178 offset:10240
	ds_read_b128 v[116:119], v178 offset:3072
	ds_read_b128 v[158:161], v178 offset:11264
	ds_read_b128 v[120:123], v178 offset:4096
	ds_read_b128 v[162:165], v178 offset:12288
	ds_read_b128 v[124:127], v178 offset:5120
	ds_read_b128 v[166:169], v178 offset:13312
	ds_read_b128 v[128:131], v178 offset:6144
	ds_read_b128 v[170:173], v178 offset:14336
	ds_read_b128 v[132:135], v178 offset:7168
	ds_read_b128 v[174:177], v178 offset:15360
	s_waitcnt vmcnt(8)
	s_barrier
	s_add_i32 m0, s7, 98304
	s_nop 0
	global_load_lds_dwordx4 v[180:181], off
	v_lshl_add_u64 v[180:181], v[180:181], 0, s[98:99]
	s_add_i32 m0, s7, 106496
	s_nop 0
	global_load_lds_dwordx4 v[180:181], off
	v_lshl_add_u64 v[180:181], v[180:181], 0, s[98:99]
	s_waitcnt lgkmcnt(14)
	v_mfma_f32_16x16x32_bf16 v[32:35], v[104:107], v[0:3], 0
	v_mfma_f32_16x16x32_bf16 v[36:39], v[146:149], v[0:3], 0
	ds_read_b128 v[104:107], v178 offset:16384
	ds_read_b128 v[146:149], v178 offset:24576
	s_waitcnt lgkmcnt(14)
	v_mfma_f32_16x16x32_bf16 v[32:35], v[108:111], v[4:7], v[32:35]
	v_mfma_f32_16x16x32_bf16 v[36:39], v[150:153], v[4:7], v[36:39]
	ds_read_b128 v[108:111], v178 offset:17408
	ds_read_b128 v[150:153], v178 offset:25600
	s_waitcnt lgkmcnt(14)
	v_mfma_f32_16x16x32_bf16 v[32:35], v[112:115], v[8:11], v[32:35]
	v_mfma_f32_16x16x32_bf16 v[36:39], v[154:157], v[8:11], v[36:39]
	ds_read_b128 v[112:115], v178 offset:18432
	ds_read_b128 v[154:157], v178 offset:26624
	s_waitcnt lgkmcnt(14)
	v_mfma_f32_16x16x32_bf16 v[32:35], v[116:119], v[12:15], v[32:35]
	v_mfma_f32_16x16x32_bf16 v[36:39], v[158:161], v[12:15], v[36:39]
	ds_read_b128 v[116:119], v178 offset:19456
	ds_read_b128 v[158:161], v178 offset:27648
	s_waitcnt lgkmcnt(14)
	v_mfma_f32_16x16x32_bf16 v[32:35], v[120:123], v[16:19], v[32:35]
	v_mfma_f32_16x16x32_bf16 v[36:39], v[162:165], v[16:19], v[36:39]
	ds_read_b128 v[120:123], v178 offset:20480
	ds_read_b128 v[162:165], v178 offset:28672
	s_waitcnt lgkmcnt(14)
	v_mfma_f32_16x16x32_bf16 v[32:35], v[124:127], v[20:23], v[32:35]
	v_mfma_f32_16x16x32_bf16 v[36:39], v[166:169], v[20:23], v[36:39]
	ds_read_b128 v[124:127], v178 offset:21504
	ds_read_b128 v[166:169], v178 offset:29696
	s_waitcnt lgkmcnt(14)
	v_mfma_f32_16x16x32_bf16 v[32:35], v[128:131], v[24:27], v[32:35]
	v_mfma_f32_16x16x32_bf16 v[36:39], v[170:173], v[24:27], v[36:39]
	ds_read_b128 v[128:131], v178 offset:22528
	ds_read_b128 v[170:173], v178 offset:30720
	s_waitcnt lgkmcnt(14)
	v_mfma_f32_16x16x32_bf16 v[32:35], v[132:135], v[28:31], v[32:35]
	v_mfma_f32_16x16x32_bf16 v[36:39], v[174:177], v[28:31], v[36:39]
	ds_read_b128 v[132:135], v178 offset:23552
	ds_read_b128 v[174:177], v178 offset:31744
	s_waitcnt vmcnt(8)
	s_barrier
; __device__ __forceinline__ f32x4 mfma16(bf16x8 a, bf16x8 b, f32x4 c) { return __builtin_amdgcn_mfma_f32_16x16x32_bf16(a, b, c, 0, 0, 0); }
; __device__ __forceinline__ void mem_task(bf16_t* zb, const bf16_t* kvm_b, const bf16_t* vmt_b, int hm, int t0, int lane, bool do_store) {
;     ...
;     for (int kt = 0; kt < 16; ++kt) {
;         if (kt + 2 < 16) { const bf16_t* kp = kbase + (size_t)(((kt + 2) >> 1) * 32 + 4 * ((kt + 2) & 1)) * 2048;
; #pragma unroll
;             for (int kk = 0; kk < 8; ++kk) kfr[(kt + 2) % 3][kk] = *(const bf16x8*)(kp + kk * 32); }
;         f32x4 acc = zero4;
;         __builtin_amdgcn_s_setprio(1);
; #pragma unroll
;         for (int kk = 0; kk < 8; ++kk) acc = mfma16(kfr[kt % 3][kk], qf[kk], acc);
;         __builtin_amdgcn_s_setprio(0);
;         s[kt] = acc; }
	s_add_i32 m0, s7, 114688
	s_nop 0
	global_load_lds_dwordx4 v[180:181], off
	v_lshl_add_u64 v[180:181], v[180:181], 0, s[98:99]
	s_add_i32 m0, s7, 122880
	s_nop 0
	global_load_lds_dwordx4 v[180:181], off
	v_lshl_add_u64 v[180:181], v[180:181], 0, s[98:99]
	s_waitcnt lgkmcnt(14)
	v_mfma_f32_16x16x32_bf16 v[40:43], v[104:107], v[0:3], 0
	v_mfma_f32_16x16x32_bf16 v[44:47], v[146:149], v[0:3], 0
	ds_read_b128 v[104:107], v178 offset:32768
	ds_read_b128 v[146:149], v178 offset:40960
	s_waitcnt lgkmcnt(14)
	v_mfma_f32_16x16x32_bf16 v[40:43], v[108:111], v[4:7], v[40:43]
	v_mfma_f32_16x16x32_bf16 v[44:47], v[150:153], v[4:7], v[44:47]
	ds_read_b128 v[108:111], v178 offset:33792
	ds_read_b128 v[150:153], v178 offset:41984
	s_waitcnt lgkmcnt(14)
	v_mfma_f32_16x16x32_bf16 v[40:43], v[112:115], v[8:11], v[40:43]
	v_mfma_f32_16x16x32_bf16 v[44:47], v[154:157], v[8:11], v[44:47]
	ds_read_b128 v[112:115], v178 offset:34816
	ds_read_b128 v[154:157], v178 offset:43008
	s_waitcnt lgkmcnt(14)
	v_mfma_f32_16x16x32_bf16 v[40:43], v[116:119], v[12:15], v[40:43]
	v_mfma_f32_16x16x32_bf16 v[44:47], v[158:161], v[12:15], v[44:47]
	ds_read_b128 v[116:119], v178 offset:35840
	ds_read_b128 v[158:161], v178 offset:44032
	s_waitcnt lgkmcnt(14)
	v_mfma_f32_16x16x32_bf16 v[40:43], v[120:123], v[16:19], v[40:43]
	v_mfma_f32_16x16x32_bf16 v[44:47], v[162:165], v[16:19], v[44:47]
	ds_read_b128 v[120:123], v178 offset:36864
	ds_read_b128 v[162:165], v178 offset:45056
	s_waitcnt lgkmcnt(14)
	v_mfma_f32_16x16x32_bf16 v[40:43], v[124:127], v[20:23], v[40:43]
	v_mfma_f32_16x16x32_bf16 v[44:47], v[166:169], v[20:23], v[44:47]
	ds_read_b128 v[124:127], v178 offset:37888
	ds_read_b128 v[166:169], v178 offset:46080
	s_waitcnt lgkmcnt(14)
	v_mfma_f32_16x16x32_bf16 v[40:43], v[128:131], v[24:27], v[40:43]
	v_mfma_f32_16x16x32_bf16 v[44:47], v[170:173], v[24:27], v[44:47]
	ds_read_b128 v[128:131], v178 offset:38912
	ds_read_b128 v[170:173], v178 offset:47104
	s_waitcnt lgkmcnt(14)
	v_mfma_f32_16x16x32_bf16 v[40:43], v[132:135], v[28:31], v[40:43]
	v_mfma_f32_16x16x32_bf16 v[44:47], v[174:177], v[28:31], v[44:47]
	ds_read_b128 v[132:135], v178 offset:39936
	ds_read_b128 v[174:177], v178 offset:48128
	s_waitcnt vmcnt(8)
	s_barrier
	s_add_i32 m0, s7, 0
	s_nop 0
	global_load_lds_dwordx4 v[182:183], off
	v_lshl_add_u64 v[182:183], v[182:183], 0, s[98:99]
	s_add_i32 m0, s7, 8192
	s_nop 0
	global_load_lds_dwordx4 v[182:183], off
	v_lshl_add_u64 v[182:183], v[182:183], 0, s[98:99]
	s_waitcnt lgkmcnt(14)
	v_mfma_f32_16x16x32_bf16 v[48:51], v[104:107], v[0:3], 0
	v_mfma_f32_16x16x32_bf16 v[52:55], v[146:149], v[0:3], 0
	ds_read_b128 v[104:107], v178 offset:49152
	ds_read_b128 v[146:149], v178 offset:57344
	s_waitcnt lgkmcnt(14)
	v_mfma_f32_16x16x32_bf16 v[48:51], v[108:111], v[4:7], v[48:51]
	v_mfma_f32_16x16x32_bf16 v[52:55], v[150:153], v[4:7], v[52:55]
	ds_read_b128 v[108:111], v178 offset:50176
	ds_read_b128 v[150:153], v178 offset:58368
	s_waitcnt lgkmcnt(14)
	v_mfma_f32_16x16x32_bf16 v[48:51], v[112:115], v[8:11], v[48:51]
	v_mfma_f32_16x16x32_bf16 v[52:55], v[154:157], v[8:11], v[52:55]
	ds_read_b128 v[112:115], v178 offset:51200
	ds_read_b128 v[154:157], v178 offset:59392
	s_waitcnt lgkmcnt(14)
	v_mfma_f32_16x16x32_bf16 v[48:51], v[116:119], v[12:15], v[48:51]
	v_mfma_f32_16x16x32_bf16 v[52:55], v[158:161], v[12:15], v[52:55]
	ds_read_b128 v[116:119], v178 offset:52224
	ds_read_b128 v[158:161], v178 offset:60416
	s_waitcnt lgkmcnt(14)
	v_mfma_f32_16x16x32_bf16 v[48:51], v[120:123], v[16:19], v[48:51]
	v_mfma_f32_16x16x32_bf16 v[52:55], v[162:165], v[16:19], v[52:55]
	ds_read_b128 v[120:123], v178 offset:53248
	ds_read_b128 v[162:165], v178 offset:61440
	s_waitcnt lgkmcnt(14)
	v_mfma_f32_16x16x32_bf16 v[48:51], v[124:127], v[20:23], v[48:51]
	v_mfma_f32_16x16x32_bf16 v[52:55], v[166:169], v[20:23], v[52:55]
	ds_read_b128 v[124:127], v178 offset:54272
	ds_read_b128 v[166:169], v178 offset:62464
	s_waitcnt lgkmcnt(14)
	v_mfma_f32_16x16x32_bf16 v[48:51], v[128:131], v[24:27], v[48:51]
	v_mfma_f32_16x16x32_bf16 v[52:55], v[170:173], v[24:27], v[52:55]
	ds_read_b128 v[128:131], v178 offset:55296
	ds_read_b128 v[170:173], v178 offset:63488
	s_waitcnt lgkmcnt(14)
	v_mfma_f32_16x16x32_bf16 v[48:51], v[132:135], v[28:31], v[48:51]
	v_mfma_f32_16x16x32_bf16 v[52:55], v[174:177], v[28:31], v[52:55]
	ds_read_b128 v[132:135], v178 offset:56320
	ds_read_b128 v[174:177], v178 offset:64512
	s_waitcnt vmcnt(8)
	s_barrier
	s_add_i32 m0, s7, 16384
	s_nop 0
	global_load_lds_dwordx4 v[182:183], off
	v_lshl_add_u64 v[182:183], v[182:183], 0, s[98:99]
	s_add_i32 m0, s7, 24576
	s_nop 0
	global_load_lds_dwordx4 v[182:183], off
	v_lshl_add_u64 v[182:183], v[182:183], 0, s[98:99]
	s_waitcnt lgkmcnt(14)
	v_mfma_f32_16x16x32_bf16 v[56:59], v[104:107], v[0:3], 0
	v_mfma_f32_16x16x32_bf16 v[60:63], v[146:149], v[0:3], 0
	ds_read_b128 v[104:107], v179 offset:0
	ds_read_b128 v[146:149], v179 offset:8192
	s_waitcnt lgkmcnt(14)
	v_mfma_f32_16x16x32_bf16 v[56:59], v[108:111], v[4:7], v[56:59]
	v_mfma_f32_16x16x32_bf16 v[60:63], v[150:153], v[4:7], v[60:63]
	ds_read_b128 v[108:111], v179 offset:1024
	ds_read_b128 v[150:153], v179 offset:9216
	s_waitcnt lgkmcnt(14)
	v_mfma_f32_16x16x32_bf16 v[56:59], v[112:115], v[8:11], v[56:59]
	v_mfma_f32_16x16x32_bf16 v[60:63], v[154:157], v[8:11], v[60:63]
	ds_read_b128 v[112:115], v179 offset:2048
	ds_read_b128 v[154:157], v179 offset:10240
	s_waitcnt lgkmcnt(14)
	v_mfma_f32_16x16x32_bf16 v[56:59], v[116:119], v[12:15], v[56:59]
	v_mfma_f32_16x16x32_bf16 v[60:63], v[158:161], v[12:15], v[60:63]
	ds_read_b128 v[116:119], v179 offset:3072
	ds_read_b128 v[158:161], v179 offset:11264
	s_waitcnt lgkmcnt(14)
	v_mfma_f32_16x16x32_bf16 v[56:59], v[120:123], v[16:19], v[56:59]
	v_mfma_f32_16x16x32_bf16 v[60:63], v[162:165], v[16:19], v[60:63]
	ds_read_b128 v[120:123], v179 offset:4096
	ds_read_b128 v[162:165], v179 offset:12288
	s_waitcnt lgkmcnt(14)
	v_mfma_f32_16x16x32_bf16 v[56:59], v[124:127], v[20:23], v[56:59]
	v_mfma_f32_16x16x32_bf16 v[60:63], v[166:169], v[20:23], v[60:63]
	ds_read_b128 v[124:127], v179 offset:5120
	ds_read_b128 v[166:169], v179 offset:13312
	s_waitcnt lgkmcnt(14)
	v_mfma_f32_16x16x32_bf16 v[56:59], v[128:131], v[24:27], v[56:59]
	v_mfma_f32_16x16x32_bf16 v[60:63], v[170:173], v[24:27], v[60:63]
	ds_read_b128 v[128:131], v179 offset:6144
	ds_read_b128 v[170:173], v179 offset:14336
	s_waitcnt lgkmcnt(14)
	v_mfma_f32_16x16x32_bf16 v[56:59], v[132:135], v[28:31], v[56:59]
	v_mfma_f32_16x16x32_bf16 v[60:63], v[174:177], v[28:31], v[60:63]
	ds_read_b128 v[132:135], v179 offset:7168
	ds_read_b128 v[174:177], v179 offset:15360
	s_waitcnt vmcnt(8)
	s_barrier
; __device__ __forceinline__ f32x4 mfma16(bf16x8 a, bf16x8 b, f32x4 c) { return __builtin_amdgcn_mfma_f32_16x16x32_bf16(a, b, c, 0, 0, 0); }
; __device__ __forceinline__ void mem_task(bf16_t* zb, const bf16_t* kvm_b, const bf16_t* vmt_b, int hm, int t0, int lane, bool do_store) {
;     ...
;     for (int kt = 0; kt < 16; ++kt) {
;         if (kt + 2 < 16) { const bf16_t* kp = kbase + (size_t)(((kt + 2) >> 1) * 32 + 4 * ((kt + 2) & 1)) * 2048;
; #pragma unroll
;             for (int kk = 0; kk < 8; ++kk) kfr[(kt + 2) % 3][kk] = *(const bf16x8*)(kp + kk * 32); }
;         f32x4 acc = zero4;
;         __builtin_amdgcn_s_setprio(1);
; #pragma unroll
;         for (int kk = 0; kk < 8; ++kk) acc = mfma16(kfr[kt % 3][kk], qf[kk], acc);
;         __builtin_amdgcn_s_setprio(0);
;         s[kt] = acc; }
	s_add_i32 m0, s7, 32768
	s_nop 0
	global_load_lds_dwordx4 v[182:183], off
	v_lshl_add_u64 v[182:183], v[182:183], 0, s[98:99]
	s_add_i32 m0, s7, 40960
	s_nop 0
	global_load_lds_dwordx4 v[182:183], off
	v_lshl_add_u64 v[182:183], v[182:183], 0, s[98:99]
	s_waitcnt lgkmcnt(14)
	v_mfma_f32_16x16x32_bf16 v[72:75], v[104:107], v[0:3], 0
	v_mfma_f32_16x16x32_bf16 v[76:79], v[146:149], v[0:3], 0
	ds_read_b128 v[104:107], v179 offset:16384
	ds_read_b128 v[146:149], v179 offset:24576
	s_waitcnt lgkmcnt(14)
	v_mfma_f32_16x16x32_bf16 v[72:75], v[108:111], v[4:7], v[72:75]
	v_mfma_f32_16x16x32_bf16 v[76:79], v[150:153], v[4:7], v[76:79]
	ds_read_b128 v[108:111], v179 offset:17408
	ds_read_b128 v[150:153], v179 offset:25600
	s_waitcnt lgkmcnt(14)
	v_mfma_f32_16x16x32_bf16 v[72:75], v[112:115], v[8:11], v[72:75]
	v_mfma_f32_16x16x32_bf16 v[76:79], v[154:157], v[8:11], v[76:79]
	ds_read_b128 v[112:115], v179 offset:18432
	ds_read_b128 v[154:157], v179 offset:26624
	s_waitcnt lgkmcnt(14)
	v_mfma_f32_16x16x32_bf16 v[72:75], v[116:119], v[12:15], v[72:75]
	v_mfma_f32_16x16x32_bf16 v[76:79], v[158:161], v[12:15], v[76:79]
	ds_read_b128 v[116:119], v179 offset:19456
	ds_read_b128 v[158:161], v179 offset:27648
	s_waitcnt lgkmcnt(14)
	v_mfma_f32_16x16x32_bf16 v[72:75], v[120:123], v[16:19], v[72:75]
	v_mfma_f32_16x16x32_bf16 v[76:79], v[162:165], v[16:19], v[76:79]
	ds_read_b128 v[120:123], v179 offset:20480
	ds_read_b128 v[162:165], v179 offset:28672
	s_waitcnt lgkmcnt(14)
	v_mfma_f32_16x16x32_bf16 v[72:75], v[124:127], v[20:23], v[72:75]
	v_mfma_f32_16x16x32_bf16 v[76:79], v[166:169], v[20:23], v[76:79]
	ds_read_b128 v[124:127], v179 offset:21504
	ds_read_b128 v[166:169], v179 offset:29696
	s_waitcnt lgkmcnt(14)
	v_mfma_f32_16x16x32_bf16 v[72:75], v[128:131], v[24:27], v[72:75]
	v_mfma_f32_16x16x32_bf16 v[76:79], v[170:173], v[24:27], v[76:79]
	ds_read_b128 v[128:131], v179 offset:22528
	ds_read_b128 v[170:173], v179 offset:30720
	s_waitcnt lgkmcnt(14)
	v_mfma_f32_16x16x32_bf16 v[72:75], v[132:135], v[28:31], v[72:75]
	v_mfma_f32_16x16x32_bf16 v[76:79], v[174:177], v[28:31], v[76:79]
	ds_read_b128 v[132:135], v179 offset:23552
	ds_read_b128 v[174:177], v179 offset:31744
	s_waitcnt vmcnt(8)
	s_barrier
	s_add_i32 m0, s7, 49152
	s_nop 0
	global_load_lds_dwordx4 v[182:183], off
	v_lshl_add_u64 v[182:183], v[182:183], 0, s[98:99]
	s_add_i32 m0, s7, 57344
	s_nop 0
	global_load_lds_dwordx4 v[182:183], off
	v_lshl_add_u64 v[182:183], v[182:183], 0, s[98:99]
	s_waitcnt lgkmcnt(14)
	v_mfma_f32_16x16x32_bf16 v[80:83], v[104:107], v[0:3], 0
	v_mfma_f32_16x16x32_bf16 v[84:87], v[146:149], v[0:3], 0
	ds_read_b128 v[104:107], v179 offset:32768
	ds_read_b128 v[146:149], v179 offset:40960
	s_waitcnt lgkmcnt(14)
	v_mfma_f32_16x16x32_bf16 v[80:83], v[108:111], v[4:7], v[80:83]
	v_mfma_f32_16x16x32_bf16 v[84:87], v[150:153], v[4:7], v[84:87]
	ds_read_b128 v[108:111], v179 offset:33792
	ds_read_b128 v[150:153], v179 offset:41984
	s_waitcnt lgkmcnt(14)
	v_mfma_f32_16x16x32_bf16 v[80:83], v[112:115], v[8:11], v[80:83]
	v_mfma_f32_16x16x32_bf16 v[84:87], v[154:157], v[8:11], v[84:87]
	ds_read_b128 v[112:115], v179 offset:34816
	ds_read_b128 v[154:157], v179 offset:43008
	s_waitcnt lgkmcnt(14)
	v_mfma_f32_16x16x32_bf16 v[80:83], v[116:119], v[12:15], v[80:83]
	v_mfma_f32_16x16x32_bf16 v[84:87], v[158:161], v[12:15], v[84:87]
	ds_read_b128 v[116:119], v179 offset:35840
	ds_read_b128 v[158:161], v179 offset:44032
	s_waitcnt lgkmcnt(14)
	v_mfma_f32_16x16x32_bf16 v[80:83], v[120:123], v[16:19], v[80:83]
	v_mfma_f32_16x16x32_bf16 v[84:87], v[162:165], v[16:19], v[84:87]
	ds_read_b128 v[120:123], v179 offset:36864
	ds_read_b128 v[162:165], v179 offset:45056
	s_waitcnt lgkmcnt(14)
	v_mfma_f32_16x16x32_bf16 v[80:83], v[124:127], v[20:23], v[80:83]
	v_mfma_f32_16x16x32_bf16 v[84:87], v[166:169], v[20:23], v[84:87]
	ds_read_b128 v[124:127], v179 offset:37888
	ds_read_b128 v[166:169], v179 offset:46080
	s_waitcnt lgkmcnt(14)
	v_mfma_f32_16x16x32_bf16 v[80:83], v[128:131], v[24:27], v[80:83]
	v_mfma_f32_16x16x32_bf16 v[84:87], v[170:173], v[24:27], v[84:87]
	ds_read_b128 v[128:131], v179 offset:38912
	ds_read_b128 v[170:173], v179 offset:47104
	s_waitcnt lgkmcnt(14)
	v_mfma_f32_16x16x32_bf16 v[80:83], v[132:135], v[28:31], v[80:83]
	v_mfma_f32_16x16x32_bf16 v[84:87], v[174:177], v[28:31], v[84:87]
	ds_read_b128 v[132:135], v179 offset:39936
	ds_read_b128 v[174:177], v179 offset:48128
	s_waitcnt vmcnt(8)
	s_barrier
	s_add_i32 m0, s7, 65536
	s_nop 0
	global_load_lds_dwordx4 v[182:183], off
	v_lshl_add_u64 v[182:183], v[182:183], 0, s[98:99]
	s_add_i32 m0, s7, 73728
	s_nop 0
	global_load_lds_dwordx4 v[182:183], off
	v_lshl_add_u64 v[182:183], v[182:183], 0, s[98:99]
	s_waitcnt lgkmcnt(14)
	v_mfma_f32_16x16x32_bf16 v[88:91], v[104:107], v[0:3], 0
	v_mfma_f32_16x16x32_bf16 v[92:95], v[146:149], v[0:3], 0
	ds_read_b128 v[104:107], v179 offset:49152
	ds_read_b128 v[146:149], v179 offset:57344
	s_waitcnt lgkmcnt(14)
	v_mfma_f32_16x16x32_bf16 v[88:91], v[108:111], v[4:7], v[88:91]
	v_mfma_f32_16x16x32_bf16 v[92:95], v[150:153], v[4:7], v[92:95]
	ds_read_b128 v[108:111], v179 offset:50176
	ds_read_b128 v[150:153], v179 offset:58368
	s_waitcnt lgkmcnt(14)
	v_mfma_f32_16x16x32_bf16 v[88:91], v[112:115], v[8:11], v[88:91]
	v_mfma_f32_16x16x32_bf16 v[92:95], v[154:157], v[8:11], v[92:95]
	ds_read_b128 v[112:115], v179 offset:51200
	ds_read_b128 v[154:157], v179 offset:59392
	s_waitcnt lgkmcnt(14)
	v_mfma_f32_16x16x32_bf16 v[88:91], v[116:119], v[12:15], v[88:91]
	v_mfma_f32_16x16x32_bf16 v[92:95], v[158:161], v[12:15], v[92:95]
	ds_read_b128 v[116:119], v179 offset:52224
	ds_read_b128 v[158:161], v179 offset:60416
	s_waitcnt lgkmcnt(14)
	v_mfma_f32_16x16x32_bf16 v[88:91], v[120:123], v[16:19], v[88:91]
	v_mfma_f32_16x16x32_bf16 v[92:95], v[162:165], v[16:19], v[92:95]
	ds_read_b128 v[120:123], v179 offset:53248
	ds_read_b128 v[162:165], v179 offset:61440
	s_waitcnt lgkmcnt(14)
	v_mfma_f32_16x16x32_bf16 v[88:91], v[124:127], v[20:23], v[88:91]
	v_mfma_f32_16x16x32_bf16 v[92:95], v[166:169], v[20:23], v[92:95]
	ds_read_b128 v[124:127], v179 offset:54272
	ds_read_b128 v[166:169], v179 offset:62464
	s_waitcnt lgkmcnt(14)
	v_mfma_f32_16x16x32_bf16 v[88:91], v[128:131], v[24:27], v[88:91]
	v_mfma_f32_16x16x32_bf16 v[92:95], v[170:173], v[24:27], v[92:95]
	ds_read_b128 v[128:131], v179 offset:55296
	ds_read_b128 v[170:173], v179 offset:63488
	s_waitcnt lgkmcnt(14)
	v_mfma_f32_16x16x32_bf16 v[88:91], v[132:135], v[28:31], v[88:91]
	v_mfma_f32_16x16x32_bf16 v[92:95], v[174:177], v[28:31], v[92:95]
	ds_read_b128 v[132:135], v179 offset:56320
	ds_read_b128 v[174:177], v179 offset:64512
	s_waitcnt vmcnt(8)
	s_barrier
; __device__ __forceinline__ f32x4 mfma16(bf16x8 a, bf16x8 b, f32x4 c) { return __builtin_amdgcn_mfma_f32_16x16x32_bf16(a, b, c, 0, 0, 0); }
; __device__ __forceinline__ void mem_task(bf16_t* zb, const bf16_t* kvm_b, const bf16_t* vmt_b, int hm, int t0, int lane, bool do_store) {
;     ...
;     for (int kt = 0; kt < 16; ++kt) {
;         if (kt + 2 < 16) { const bf16_t* kp = kbase + (size_t)(((kt + 2) >> 1) * 32 + 4 * ((kt + 2) & 1)) * 2048;
; #pragma unroll
;             for (int kk = 0; kk < 8; ++kk) kfr[(kt + 2) % 3][kk] = *(const bf16x8*)(kp + kk * 32); }
;         f32x4 acc = zero4;
;         __builtin_amdgcn_s_setprio(1);
; #pragma unroll
;         for (int kk = 0; kk < 8; ++kk) acc = mfma16(kfr[kt % 3][kk], qf[kk], acc);
;         __builtin_amdgcn_s_setprio(0);
;         s[kt] = acc; }
;     float l = 0.f;
; #pragma unroll
;     for (int kt = 0; kt < 16; ++kt)
; #pragma unroll
;         for (int j = 0; j < 4; ++j) { s[kt][j] = __builtin_amdgcn_exp2f(s[kt][j]); l += s[kt][j]; }
	s_add_i32 m0, s7, 81920
	s_nop 0
	global_load_lds_dwordx4 v[182:183], off
	v_lshl_add_u64 v[182:183], v[182:183], 0, s[98:99]
	s_add_i32 m0, s7, 90112
	s_nop 0
	global_load_lds_dwordx4 v[182:183], off
	v_lshl_add_u64 v[182:183], v[182:183], 0, s[98:99]
	s_waitcnt lgkmcnt(14)
	v_mfma_f32_16x16x32_bf16 v[96:99], v[104:107], v[0:3], 0
	v_mfma_f32_16x16x32_bf16 v[100:103], v[146:149], v[0:3], 0
	ds_read_b128 v[104:107], v178 offset:0
	ds_read_b128 v[146:149], v178 offset:8192
	s_waitcnt lgkmcnt(14)
	v_mfma_f32_16x16x32_bf16 v[96:99], v[108:111], v[4:7], v[96:99]
	v_mfma_f32_16x16x32_bf16 v[100:103], v[150:153], v[4:7], v[100:103]
	ds_read_b128 v[108:111], v178 offset:1024
	ds_read_b128 v[150:153], v178 offset:9216
	s_waitcnt lgkmcnt(14)
	v_mfma_f32_16x16x32_bf16 v[96:99], v[112:115], v[8:11], v[96:99]
	v_mfma_f32_16x16x32_bf16 v[100:103], v[154:157], v[8:11], v[100:103]
	ds_read_b128 v[112:115], v178 offset:2048
	ds_read_b128 v[154:157], v178 offset:10240
	s_waitcnt lgkmcnt(14)
	v_mfma_f32_16x16x32_bf16 v[96:99], v[116:119], v[12:15], v[96:99]
	v_mfma_f32_16x16x32_bf16 v[100:103], v[158:161], v[12:15], v[100:103]
	ds_read_b128 v[116:119], v178 offset:3072
	ds_read_b128 v[158:161], v178 offset:11264
	s_waitcnt lgkmcnt(14)
	v_mfma_f32_16x16x32_bf16 v[96:99], v[120:123], v[16:19], v[96:99]
	v_mfma_f32_16x16x32_bf16 v[100:103], v[162:165], v[16:19], v[100:103]
	ds_read_b128 v[120:123], v178 offset:4096
	ds_read_b128 v[162:165], v178 offset:12288
	s_waitcnt lgkmcnt(14)
	v_mfma_f32_16x16x32_bf16 v[96:99], v[124:127], v[20:23], v[96:99]
	v_mfma_f32_16x16x32_bf16 v[100:103], v[166:169], v[20:23], v[100:103]
	ds_read_b128 v[124:127], v178 offset:5120
	ds_read_b128 v[166:169], v178 offset:13312
	s_waitcnt lgkmcnt(14)
	v_mfma_f32_16x16x32_bf16 v[96:99], v[128:131], v[24:27], v[96:99]
	v_mfma_f32_16x16x32_bf16 v[100:103], v[170:173], v[24:27], v[100:103]
	ds_read_b128 v[128:131], v178 offset:6144
	ds_read_b128 v[170:173], v178 offset:14336
	s_waitcnt lgkmcnt(14)
	v_mfma_f32_16x16x32_bf16 v[96:99], v[132:135], v[28:31], v[96:99]
	v_mfma_f32_16x16x32_bf16 v[100:103], v[174:177], v[28:31], v[100:103]
	ds_read_b128 v[132:135], v178 offset:7168
	ds_read_b128 v[174:177], v178 offset:15360
	s_nop 7
	s_nop 7
	v_exp_f32_e32 v32, v32
	v_exp_f32_e32 v33, v33
	v_add_f32_e32 v190, 0, v32
	v_exp_f32_e32 v34, v34
	v_add_f32_e32 v190, v190, v33
	v_exp_f32_e32 v35, v35
	v_add_f32_e32 v190, v190, v34
	v_exp_f32_e32 v36, v36
	v_add_f32_e32 v190, v190, v35
	v_exp_f32_e32 v37, v37
	v_add_f32_e32 v190, v190, v36
	v_exp_f32_e32 v38, v38
	v_add_f32_e32 v190, v190, v37
	v_exp_f32_e32 v39, v39
	v_add_f32_e32 v190, v190, v38
	v_exp_f32_e32 v40, v40
	v_add_f32_e32 v190, v190, v39
	v_exp_f32_e32 v41, v41
	v_add_f32_e32 v190, v190, v40
	v_exp_f32_e32 v42, v42
	v_add_f32_e32 v190, v190, v41
	v_exp_f32_e32 v43, v43
	v_add_f32_e32 v190, v190, v42
	v_exp_f32_e32 v44, v44
	v_add_f32_e32 v190, v190, v43
	v_exp_f32_e32 v45, v45
	v_add_f32_e32 v190, v190, v44
	v_exp_f32_e32 v46, v46
	v_add_f32_e32 v190, v190, v45
	v_exp_f32_e32 v47, v47
	v_add_f32_e32 v190, v190, v46
	v_exp_f32_e32 v48, v48
	v_add_f32_e32 v190, v190, v47
	v_exp_f32_e32 v49, v49
	v_add_f32_e32 v190, v190, v48
	v_exp_f32_e32 v50, v50
	v_add_f32_e32 v190, v190, v49
	v_exp_f32_e32 v51, v51
	v_add_f32_e32 v190, v190, v50
	v_exp_f32_e32 v52, v52
	v_add_f32_e32 v190, v190, v51
	v_exp_f32_e32 v53, v53
	v_add_f32_e32 v190, v190, v52
	v_exp_f32_e32 v54, v54
	v_add_f32_e32 v190, v190, v53
	v_exp_f32_e32 v55, v55
	v_add_f32_e32 v190, v190, v54
	v_exp_f32_e32 v56, v56
	v_add_f32_e32 v190, v190, v55
	v_exp_f32_e32 v57, v57
	v_add_f32_e32 v190, v190, v56
	v_exp_f32_e32 v58, v58
	v_add_f32_e32 v190, v190, v57
	v_exp_f32_e32 v59, v59
	v_add_f32_e32 v190, v190, v58
	v_exp_f32_e32 v60, v60
	v_add_f32_e32 v190, v190, v59
	v_exp_f32_e32 v61, v61
	v_add_f32_e32 v190, v190, v60
	v_exp_f32_e32 v62, v62
	v_add_f32_e32 v190, v190, v61
	v_exp_f32_e32 v63, v63
	v_add_f32_e32 v190, v190, v62
	v_exp_f32_e32 v72, v72
	v_add_f32_e32 v190, v190, v63
	v_exp_f32_e32 v73, v73
	v_add_f32_e32 v190, v190, v72
	v_exp_f32_e32 v74, v74
	v_add_f32_e32 v190, v190, v73
	v_exp_f32_e32 v75, v75
	v_add_f32_e32 v190, v190, v74
	v_exp_f32_e32 v76, v76
	v_add_f32_e32 v190, v190, v75
	v_exp_f32_e32 v77, v77
	v_add_f32_e32 v190, v190, v76
	v_exp_f32_e32 v78, v78
	v_add_f32_e32 v190, v190, v77
	v_exp_f32_e32 v79, v79
	v_add_f32_e32 v190, v190, v78
	v_exp_f32_e32 v80, v80
	v_add_f32_e32 v190, v190, v79
	v_exp_f32_e32 v81, v81
	v_add_f32_e32 v190, v190, v80
	v_exp_f32_e32 v82, v82
	v_add_f32_e32 v190, v190, v81
	v_exp_f32_e32 v83, v83
	v_add_f32_e32 v190, v190, v82
	v_exp_f32_e32 v84, v84
	v_add_f32_e32 v190, v190, v83
	v_exp_f32_e32 v85, v85
	v_add_f32_e32 v190, v190, v84
	v_exp_f32_e32 v86, v86
	v_add_f32_e32 v190, v190, v85
	v_exp_f32_e32 v87, v87
	v_add_f32_e32 v190, v190, v86
	v_exp_f32_e32 v88, v88
	v_add_f32_e32 v190, v190, v87
	v_exp_f32_e32 v89, v89
	v_add_f32_e32 v190, v190, v88
	v_exp_f32_e32 v90, v90
	v_add_f32_e32 v190, v190, v89
	v_exp_f32_e32 v91, v91
	v_add_f32_e32 v190, v190, v90
	v_exp_f32_e32 v92, v92
	v_add_f32_e32 v190, v190, v91
	v_exp_f32_e32 v93, v93
	v_add_f32_e32 v190, v190, v92
	v_exp_f32_e32 v94, v94
	v_add_f32_e32 v190, v190, v93
	v_exp_f32_e32 v95, v95
	v_add_f32_e32 v190, v190, v94
	v_exp_f32_e32 v96, v96
	v_add_f32_e32 v190, v190, v95
	v_exp_f32_e32 v97, v97
	v_add_f32_e32 v190, v190, v96
	v_exp_f32_e32 v98, v98
	v_add_f32_e32 v190, v190, v97
	v_exp_f32_e32 v99, v99
	v_add_f32_e32 v190, v190, v98
	v_exp_f32_e32 v100, v100
	v_add_f32_e32 v190, v190, v99
	v_exp_f32_e32 v101, v101
	v_add_f32_e32 v190, v190, v100
	v_exp_f32_e32 v102, v102
; __device__ __forceinline__ unsigned cvt_pk_bf16(float lo, float hi) { unsigned r; asm volatile("v_cvt_pk_bf16_f32 %0, %1, %2" : "=v"(r) : "v"(lo), "v"(hi)); return r; }
; __device__ __forceinline__ f32x4 mfma16(bf16x8 a, bf16x8 b, f32x4 c) { return __builtin_amdgcn_mfma_f32_16x16x32_bf16(a, b, c, 0, 0, 0); }
; __device__ __forceinline__ float x16sum(float x) { auto r = __builtin_amdgcn_permlane16_swap(__float_as_uint(x), __float_as_uint(x), false, false); return __uint_as_float(r[0]) + __uint_as_float(r[1]); }
; __device__ __forceinline__ float x32sum(float x) { auto r = __builtin_amdgcn_permlane32_swap(__float_as_uint(x), __float_as_uint(x), false, false); return __uint_as_float(r[0]) + __uint_as_float(r[1]); }
; __device__ __forceinline__ void mem_task(bf16_t* zb, const bf16_t* kvm_b, const bf16_t* vmt_b, int hm, int t0, int lane, bool do_store) {
;     ...
;         for (int j = 0; j < 4; ++j) { s[kt][j] = __builtin_amdgcn_exp2f(s[kt][j]); l += s[kt][j]; }
;     l = x16sum(l); l = x32sum(l);
;     const float il = 1.0f / l;
;     bf16x8 pf[8];
; #pragma unroll
;     for (int kp = 0; kp < 8; ++kp) { u32x4 w; w.x = cvt_pk_bf16(s[2 * kp][0], s[2 * kp][1]); w.y = cvt_pk_bf16(s[2 * kp][2], s[2 * kp][3]); w.z = cvt_pk_bf16(s[2 * kp + 1][0], s[2 * kp + 1][1]); w.w = cvt_pk_bf16(s[2 * kp + 1][2], s[2 * kp + 1][3]); pf[kp] = __builtin_bit_cast(bf16x8, w); }
;     const bf16_t* vbase = vmt_b + (size_t)(hm * 256 + n) * 256 + 8 * fq;
;     bf16x8 vfr[3][8];
; #pragma unroll
;     for (int kp = 0; kp < 8; ++kp) vfr[0][kp] = *(const bf16x8*)(vbase + kp * 32);
;     { const bf16_t* vp = vbase + (size_t)16 * 256;
; #pragma unroll
;       for (int kp = 0; kp < 8; ++kp) vfr[1][kp] = *(const bf16x8*)(vp + kp * 32); }
; #pragma unroll
;     for (int dt = 0; dt < 16; ++dt) {
;         if (dt + 2 < 16) { const bf16_t* vp = vbase + (size_t)((dt + 2) * 16) * 256;
; #pragma unroll
;             for (int kp = 0; kp < 8; ++kp) vfr[(dt + 2) % 3][kp] = *(const bf16x8*)(vp + kp * 32); }
;         f32x4 acc = zero4;
;         __builtin_amdgcn_s_setprio(1);
; #pragma unroll
;         for (int kp = 0; kp < 8; ++kp) acc = mfma16(vfr[dt % 3][kp], pf[kp], acc);
;         __builtin_amdgcn_s_setprio(0);
;         u32x2 w; w.x = cvt_pk_bf16(acc[0] * il, acc[1] * il); w.y = cvt_pk_bf16(acc[2] * il, acc[3] * il); if (do_store || acc[0] == 12345.678f) *(u32x2*)(qp + dt * 16 + 4 * fq) = w; }
	v_add_f32_e32 v190, v190, v101
	v_exp_f32_e32 v103, v103
	v_add_f32_e32 v190, v190, v102
	s_nop 0
	v_add_f32_e32 v190, v190, v103
	v_mov_b32_e32 v186, v190
	s_nop 1
	v_permlane16_swap_b32_e32 v190, v186
	v_add_f32_e32 v190, v190, v186
	v_mov_b32_e32 v186, v190
	s_nop 1
	v_permlane32_swap_b32_e32 v190, v186
	v_add_f32_e32 v190, v190, v186
	v_div_scale_f32 v186, s[12:13], v190, v190, 1.0
	v_rcp_f32_e32 v187, v186
	s_nop 0
	v_fma_f32 v188, -v186, v187, 1.0
	v_fmac_f32_e32 v187, v188, v187
	v_div_scale_f32 v188, vcc, 1.0, v190, 1.0
	v_mul_f32_e32 v189, v188, v187
	v_fma_f32 v136, -v186, v189, v188
	v_fmac_f32_e32 v189, v136, v187
	v_fma_f32 v186, -v186, v189, v188
	s_nop 0
	v_div_fmas_f32 v186, v186, v187, v189
	v_div_fixup_f32 v191, v186, v190, 1.0
	v_cvt_pk_bf16_f32 v32, v32, v33
	v_cvt_pk_bf16_f32 v33, v34, v35
	v_cvt_pk_bf16_f32 v34, v36, v37
	v_cvt_pk_bf16_f32 v35, v38, v39
	v_cvt_pk_bf16_f32 v40, v40, v41
	v_cvt_pk_bf16_f32 v41, v42, v43
	v_cvt_pk_bf16_f32 v42, v44, v45
	v_cvt_pk_bf16_f32 v43, v46, v47
	v_cvt_pk_bf16_f32 v48, v48, v49
	v_cvt_pk_bf16_f32 v49, v50, v51
	v_cvt_pk_bf16_f32 v50, v52, v53
	v_cvt_pk_bf16_f32 v51, v54, v55
	v_cvt_pk_bf16_f32 v56, v56, v57
	v_cvt_pk_bf16_f32 v57, v58, v59
	v_cvt_pk_bf16_f32 v58, v60, v61
	v_cvt_pk_bf16_f32 v59, v62, v63
	v_cvt_pk_bf16_f32 v72, v72, v73
	v_cvt_pk_bf16_f32 v73, v74, v75
	v_cvt_pk_bf16_f32 v74, v76, v77
	v_cvt_pk_bf16_f32 v75, v78, v79
	v_cvt_pk_bf16_f32 v80, v80, v81
	v_cvt_pk_bf16_f32 v81, v82, v83
	v_cvt_pk_bf16_f32 v82, v84, v85
	v_cvt_pk_bf16_f32 v83, v86, v87
	v_cvt_pk_bf16_f32 v88, v88, v89
	v_cvt_pk_bf16_f32 v89, v90, v91
	v_cvt_pk_bf16_f32 v90, v92, v93
	v_cvt_pk_bf16_f32 v91, v94, v95
	v_cvt_pk_bf16_f32 v96, v96, v97
	v_cvt_pk_bf16_f32 v97, v98, v99
	v_cvt_pk_bf16_f32 v98, v100, v101
	v_cvt_pk_bf16_f32 v99, v102, v103
	s_waitcnt vmcnt(8)
	s_barrier
	s_add_i32 m0, s7, 98304
	s_nop 0
	global_load_lds_dwordx4 v[182:183], off
	v_lshl_add_u64 v[182:183], v[182:183], 0, s[98:99]
	s_add_i32 m0, s7, 106496
	s_nop 0
	global_load_lds_dwordx4 v[182:183], off
	v_lshl_add_u64 v[182:183], v[182:183], 0, s[98:99]
	s_waitcnt lgkmcnt(14)
	v_mfma_f32_16x16x32_bf16 v[192:195], v[104:107], v[32:35], 0
	v_mfma_f32_16x16x32_bf16 v[196:199], v[146:149], v[32:35], 0
	ds_read_b128 v[104:107], v178 offset:16384
	ds_read_b128 v[146:149], v178 offset:24576
	s_waitcnt lgkmcnt(14)
	v_mfma_f32_16x16x32_bf16 v[192:195], v[108:111], v[40:43], v[192:195]
	v_mfma_f32_16x16x32_bf16 v[196:199], v[150:153], v[40:43], v[196:199]
	ds_read_b128 v[108:111], v178 offset:17408
	ds_read_b128 v[150:153], v178 offset:25600
	s_waitcnt lgkmcnt(14)
	v_mfma_f32_16x16x32_bf16 v[192:195], v[112:115], v[48:51], v[192:195]
	v_mfma_f32_16x16x32_bf16 v[196:199], v[154:157], v[48:51], v[196:199]
	ds_read_b128 v[112:115], v178 offset:18432
	ds_read_b128 v[154:157], v178 offset:26624
	s_waitcnt lgkmcnt(14)
	v_mfma_f32_16x16x32_bf16 v[192:195], v[116:119], v[56:59], v[192:195]
	v_mfma_f32_16x16x32_bf16 v[196:199], v[158:161], v[56:59], v[196:199]
	ds_read_b128 v[116:119], v178 offset:19456
	ds_read_b128 v[158:161], v178 offset:27648
	s_waitcnt lgkmcnt(14)
	v_mfma_f32_16x16x32_bf16 v[192:195], v[120:123], v[72:75], v[192:195]
	v_mfma_f32_16x16x32_bf16 v[196:199], v[162:165], v[72:75], v[196:199]
	ds_read_b128 v[120:123], v178 offset:20480
	ds_read_b128 v[162:165], v178 offset:28672
	s_waitcnt lgkmcnt(14)
	v_mfma_f32_16x16x32_bf16 v[192:195], v[124:127], v[80:83], v[192:195]
	v_mfma_f32_16x16x32_bf16 v[196:199], v[166:169], v[80:83], v[196:199]
	ds_read_b128 v[124:127], v178 offset:21504
	ds_read_b128 v[166:169], v178 offset:29696
	s_waitcnt lgkmcnt(14)
	v_mfma_f32_16x16x32_bf16 v[192:195], v[128:131], v[88:91], v[192:195]
	v_mfma_f32_16x16x32_bf16 v[196:199], v[170:173], v[88:91], v[196:199]
	ds_read_b128 v[128:131], v178 offset:22528
	ds_read_b128 v[170:173], v178 offset:30720
	s_waitcnt lgkmcnt(14)
	v_mfma_f32_16x16x32_bf16 v[192:195], v[132:135], v[96:99], v[192:195]
	v_mfma_f32_16x16x32_bf16 v[196:199], v[174:177], v[96:99], v[196:199]
	ds_read_b128 v[132:135], v178 offset:23552
	ds_read_b128 v[174:177], v178 offset:31744
	s_waitcnt vmcnt(8)
	s_barrier
	s_add_i32 m0, s7, 114688
	s_nop 0
	global_load_lds_dwordx4 v[182:183], off
	v_lshl_add_u64 v[182:183], v[182:183], 0, s[98:99]
	s_add_i32 m0, s7, 122880
	s_nop 0
	global_load_lds_dwordx4 v[182:183], off
	v_lshl_add_u64 v[182:183], v[182:183], 0, s[98:99]
	s_waitcnt lgkmcnt(14)
	v_mfma_f32_16x16x32_bf16 v[206:209], v[104:107], v[32:35], 0
	v_mfma_f32_16x16x32_bf16 v[210:213], v[146:149], v[32:35], 0
	ds_read_b128 v[104:107], v178 offset:32768
	ds_read_b128 v[146:149], v178 offset:40960
	s_waitcnt lgkmcnt(14)
	v_mfma_f32_16x16x32_bf16 v[206:209], v[108:111], v[40:43], v[206:209]
	v_mfma_f32_16x16x32_bf16 v[210:213], v[150:153], v[40:43], v[210:213]
	ds_read_b128 v[108:111], v178 offset:33792
	ds_read_b128 v[150:153], v178 offset:41984
	s_waitcnt lgkmcnt(14)
	v_mfma_f32_16x16x32_bf16 v[206:209], v[112:115], v[48:51], v[206:209]
	v_mfma_f32_16x16x32_bf16 v[210:213], v[154:157], v[48:51], v[210:213]
	ds_read_b128 v[112:115], v178 offset:34816
	ds_read_b128 v[154:157], v178 offset:43008
	s_waitcnt lgkmcnt(14)
	v_mfma_f32_16x16x32_bf16 v[206:209], v[116:119], v[56:59], v[206:209]
	v_mfma_f32_16x16x32_bf16 v[210:213], v[158:161], v[56:59], v[210:213]
	ds_read_b128 v[116:119], v178 offset:35840
	ds_read_b128 v[158:161], v178 offset:44032
	s_waitcnt lgkmcnt(14)
	v_mfma_f32_16x16x32_bf16 v[206:209], v[120:123], v[72:75], v[206:209]
	v_mfma_f32_16x16x32_bf16 v[210:213], v[162:165], v[72:75], v[210:213]
	ds_read_b128 v[120:123], v178 offset:36864
	ds_read_b128 v[162:165], v178 offset:45056
	s_waitcnt lgkmcnt(14)
	v_mfma_f32_16x16x32_bf16 v[206:209], v[124:127], v[80:83], v[206:209]
	v_mfma_f32_16x16x32_bf16 v[210:213], v[166:169], v[80:83], v[210:213]
	ds_read_b128 v[124:127], v178 offset:37888
	ds_read_b128 v[166:169], v178 offset:46080
	s_waitcnt lgkmcnt(14)
	v_mfma_f32_16x16x32_bf16 v[206:209], v[128:131], v[88:91], v[206:209]
	v_mfma_f32_16x16x32_bf16 v[210:213], v[170:173], v[88:91], v[210:213]
	ds_read_b128 v[128:131], v178 offset:38912
	ds_read_b128 v[170:173], v178 offset:47104
	s_waitcnt lgkmcnt(14)
	v_mfma_f32_16x16x32_bf16 v[206:209], v[132:135], v[96:99], v[206:209]
	v_mfma_f32_16x16x32_bf16 v[210:213], v[174:177], v[96:99], v[210:213]
	ds_read_b128 v[132:135], v178 offset:39936
	ds_read_b128 v[174:177], v178 offset:48128
	v_mul_f32_e32 v192, v191, v192
	v_mul_f32_e32 v193, v191, v193
	v_mul_f32_e32 v194, v191, v194
	v_mul_f32_e32 v195, v191, v195
	v_cvt_pk_bf16_f32 v192, v192, v193
	v_cvt_pk_bf16_f32 v193, v194, v195
	global_store_dwordx2 v[184:185], v[192:193], off
	v_mul_f32_e32 v196, v191, v196
	v_mul_f32_e32 v197, v191, v197
	v_mul_f32_e32 v198, v191, v198
	v_mul_f32_e32 v199, v191, v199
	v_cvt_pk_bf16_f32 v196, v196, v197
	v_cvt_pk_bf16_f32 v197, v198, v199
	global_store_dwordx2 v[184:185], v[196:197], off offset:32
	s_waitcnt vmcnt(10)
	s_barrier
; __device__ __forceinline__ unsigned cvt_pk_bf16(float lo, float hi) { unsigned r; asm volatile("v_cvt_pk_bf16_f32 %0, %1, %2" : "=v"(r) : "v"(lo), "v"(hi)); return r; }
; __device__ __forceinline__ f32x4 mfma16(bf16x8 a, bf16x8 b, f32x4 c) { return __builtin_amdgcn_mfma_f32_16x16x32_bf16(a, b, c, 0, 0, 0); }
; __device__ __forceinline__ void mem_task(bf16_t* zb, const bf16_t* kvm_b, const bf16_t* vmt_b, int hm, int t0, int lane, bool do_store) {
;     ...
; #pragma unroll
;     for (int dt = 0; dt < 16; ++dt) {
;         if (dt + 2 < 16) { const bf16_t* vp = vbase + (size_t)((dt + 2) * 16) * 256;
; #pragma unroll
;             for (int kp = 0; kp < 8; ++kp) vfr[(dt + 2) % 3][kp] = *(const bf16x8*)(vp + kp * 32); }
;         f32x4 acc = zero4;
;         __builtin_amdgcn_s_setprio(1);
; #pragma unroll
;         for (int kp = 0; kp < 8; ++kp) acc = mfma16(vfr[dt % 3][kp], pf[kp], acc);
;         __builtin_amdgcn_s_setprio(0);
;         u32x2 w; w.x = cvt_pk_bf16(acc[0] * il, acc[1] * il); w.y = cvt_pk_bf16(acc[2] * il, acc[3] * il); if (do_store || acc[0] == 12345.678f) *(u32x2*)(qp + dt * 16 + 4 * fq) = w; }
	s_waitcnt lgkmcnt(14)
	v_mfma_f32_16x16x32_bf16 v[192:195], v[104:107], v[32:35], 0
	v_mfma_f32_16x16x32_bf16 v[196:199], v[146:149], v[32:35], 0
	ds_read_b128 v[104:107], v178 offset:49152
	ds_read_b128 v[146:149], v178 offset:57344
	s_waitcnt lgkmcnt(14)
	v_mfma_f32_16x16x32_bf16 v[192:195], v[108:111], v[40:43], v[192:195]
	v_mfma_f32_16x16x32_bf16 v[196:199], v[150:153], v[40:43], v[196:199]
	ds_read_b128 v[108:111], v178 offset:50176
	ds_read_b128 v[150:153], v178 offset:58368
	s_waitcnt lgkmcnt(14)
	v_mfma_f32_16x16x32_bf16 v[192:195], v[112:115], v[48:51], v[192:195]
	v_mfma_f32_16x16x32_bf16 v[196:199], v[154:157], v[48:51], v[196:199]
	ds_read_b128 v[112:115], v178 offset:51200
	ds_read_b128 v[154:157], v178 offset:59392
	s_waitcnt lgkmcnt(14)
	v_mfma_f32_16x16x32_bf16 v[192:195], v[116:119], v[56:59], v[192:195]
	v_mfma_f32_16x16x32_bf16 v[196:199], v[158:161], v[56:59], v[196:199]
	ds_read_b128 v[116:119], v178 offset:52224
	ds_read_b128 v[158:161], v178 offset:60416
	s_waitcnt lgkmcnt(14)
	v_mfma_f32_16x16x32_bf16 v[192:195], v[120:123], v[72:75], v[192:195]
	v_mfma_f32_16x16x32_bf16 v[196:199], v[162:165], v[72:75], v[196:199]
	ds_read_b128 v[120:123], v178 offset:53248
	ds_read_b128 v[162:165], v178 offset:61440
	s_waitcnt lgkmcnt(14)
	v_mfma_f32_16x16x32_bf16 v[192:195], v[124:127], v[80:83], v[192:195]
	v_mfma_f32_16x16x32_bf16 v[196:199], v[166:169], v[80:83], v[196:199]
	ds_read_b128 v[124:127], v178 offset:54272
	ds_read_b128 v[166:169], v178 offset:62464
	s_waitcnt lgkmcnt(14)
	v_mfma_f32_16x16x32_bf16 v[192:195], v[128:131], v[88:91], v[192:195]
	v_mfma_f32_16x16x32_bf16 v[196:199], v[170:173], v[88:91], v[196:199]
	ds_read_b128 v[128:131], v178 offset:55296
	ds_read_b128 v[170:173], v178 offset:63488
	s_waitcnt lgkmcnt(14)
	v_mfma_f32_16x16x32_bf16 v[192:195], v[132:135], v[96:99], v[192:195]
	v_mfma_f32_16x16x32_bf16 v[196:199], v[174:177], v[96:99], v[196:199]
	ds_read_b128 v[132:135], v178 offset:56320
	ds_read_b128 v[174:177], v178 offset:64512
	v_mul_f32_e32 v206, v191, v206
	v_mul_f32_e32 v207, v191, v207
	v_mul_f32_e32 v208, v191, v208
	v_mul_f32_e32 v209, v191, v209
	v_cvt_pk_bf16_f32 v206, v206, v207
	v_cvt_pk_bf16_f32 v207, v208, v209
	global_store_dwordx2 v[184:185], v[206:207], off offset:64
	v_mul_f32_e32 v210, v191, v210
	v_mul_f32_e32 v211, v191, v211
	v_mul_f32_e32 v212, v191, v212
	v_mul_f32_e32 v213, v191, v213
	v_cvt_pk_bf16_f32 v210, v210, v211
	v_cvt_pk_bf16_f32 v211, v212, v213
	global_store_dwordx2 v[184:185], v[210:211], off offset:96
	s_waitcnt vmcnt(10)
	s_barrier
	s_waitcnt lgkmcnt(14)
	v_mfma_f32_16x16x32_bf16 v[206:209], v[104:107], v[32:35], 0
	v_mfma_f32_16x16x32_bf16 v[210:213], v[146:149], v[32:35], 0
	ds_read_b128 v[104:107], v179 offset:0
	ds_read_b128 v[146:149], v179 offset:8192
	s_waitcnt lgkmcnt(14)
	v_mfma_f32_16x16x32_bf16 v[206:209], v[108:111], v[40:43], v[206:209]
	v_mfma_f32_16x16x32_bf16 v[210:213], v[150:153], v[40:43], v[210:213]
	ds_read_b128 v[108:111], v179 offset:1024
	ds_read_b128 v[150:153], v179 offset:9216
	s_waitcnt lgkmcnt(14)
	v_mfma_f32_16x16x32_bf16 v[206:209], v[112:115], v[48:51], v[206:209]
	v_mfma_f32_16x16x32_bf16 v[210:213], v[154:157], v[48:51], v[210:213]
	ds_read_b128 v[112:115], v179 offset:2048
	ds_read_b128 v[154:157], v179 offset:10240
	s_waitcnt lgkmcnt(14)
	v_mfma_f32_16x16x32_bf16 v[206:209], v[116:119], v[56:59], v[206:209]
	v_mfma_f32_16x16x32_bf16 v[210:213], v[158:161], v[56:59], v[210:213]
	ds_read_b128 v[116:119], v179 offset:3072
	ds_read_b128 v[158:161], v179 offset:11264
	s_waitcnt lgkmcnt(14)
	v_mfma_f32_16x16x32_bf16 v[206:209], v[120:123], v[72:75], v[206:209]
	v_mfma_f32_16x16x32_bf16 v[210:213], v[162:165], v[72:75], v[210:213]
	ds_read_b128 v[120:123], v179 offset:4096
	ds_read_b128 v[162:165], v179 offset:12288
	s_waitcnt lgkmcnt(14)
	v_mfma_f32_16x16x32_bf16 v[206:209], v[124:127], v[80:83], v[206:209]
	v_mfma_f32_16x16x32_bf16 v[210:213], v[166:169], v[80:83], v[210:213]
	ds_read_b128 v[124:127], v179 offset:5120
	ds_read_b128 v[166:169], v179 offset:13312
	s_waitcnt lgkmcnt(14)
	v_mfma_f32_16x16x32_bf16 v[206:209], v[128:131], v[88:91], v[206:209]
	v_mfma_f32_16x16x32_bf16 v[210:213], v[170:173], v[88:91], v[210:213]
	ds_read_b128 v[128:131], v179 offset:6144
	ds_read_b128 v[170:173], v179 offset:14336
	s_waitcnt lgkmcnt(14)
	v_mfma_f32_16x16x32_bf16 v[206:209], v[132:135], v[96:99], v[206:209]
	v_mfma_f32_16x16x32_bf16 v[210:213], v[174:177], v[96:99], v[210:213]
	ds_read_b128 v[132:135], v179 offset:7168
	ds_read_b128 v[174:177], v179 offset:15360
	v_mul_f32_e32 v192, v191, v192
	v_mul_f32_e32 v193, v191, v193
	v_mul_f32_e32 v194, v191, v194
	v_mul_f32_e32 v195, v191, v195
	v_cvt_pk_bf16_f32 v192, v192, v193
	v_cvt_pk_bf16_f32 v193, v194, v195
	global_store_dwordx2 v[184:185], v[192:193], off offset:128
	v_mul_f32_e32 v196, v191, v196
	v_mul_f32_e32 v197, v191, v197
	v_mul_f32_e32 v198, v191, v198
	v_mul_f32_e32 v199, v191, v199
	v_cvt_pk_bf16_f32 v196, v196, v197
	v_cvt_pk_bf16_f32 v197, v198, v199
	global_store_dwordx2 v[184:185], v[196:197], off offset:160
	s_waitcnt vmcnt(10)
	s_barrier
; __device__ __forceinline__ unsigned cvt_pk_bf16(float lo, float hi) { unsigned r; asm volatile("v_cvt_pk_bf16_f32 %0, %1, %2" : "=v"(r) : "v"(lo), "v"(hi)); return r; }
; __device__ __forceinline__ f32x4 mfma16(bf16x8 a, bf16x8 b, f32x4 c) { return __builtin_amdgcn_mfma_f32_16x16x32_bf16(a, b, c, 0, 0, 0); }
; __device__ __forceinline__ void mem_task(bf16_t* zb, const bf16_t* kvm_b, const bf16_t* vmt_b, int hm, int t0, int lane, bool do_store) {
;     ...
; #pragma unroll
;     for (int dt = 0; dt < 16; ++dt) {
;         if (dt + 2 < 16) { const bf16_t* vp = vbase + (size_t)((dt + 2) * 16) * 256;
; #pragma unroll
;             for (int kp = 0; kp < 8; ++kp) vfr[(dt + 2) % 3][kp] = *(const bf16x8*)(vp + kp * 32); }
;         f32x4 acc = zero4;
;         __builtin_amdgcn_s_setprio(1);
; #pragma unroll
;         for (int kp = 0; kp < 8; ++kp) acc = mfma16(vfr[dt % 3][kp], pf[kp], acc);
;         __builtin_amdgcn_s_setprio(0);
;         u32x2 w; w.x = cvt_pk_bf16(acc[0] * il, acc[1] * il); w.y = cvt_pk_bf16(acc[2] * il, acc[3] * il); if (do_store || acc[0] == 12345.678f) *(u32x2*)(qp + dt * 16 + 4 * fq) = w; }
	s_waitcnt lgkmcnt(14)
	v_mfma_f32_16x16x32_bf16 v[192:195], v[104:107], v[32:35], 0
	v_mfma_f32_16x16x32_bf16 v[196:199], v[146:149], v[32:35], 0
	ds_read_b128 v[104:107], v179 offset:16384
	ds_read_b128 v[146:149], v179 offset:24576
	s_waitcnt lgkmcnt(14)
	v_mfma_f32_16x16x32_bf16 v[192:195], v[108:111], v[40:43], v[192:195]
	v_mfma_f32_16x16x32_bf16 v[196:199], v[150:153], v[40:43], v[196:199]
	ds_read_b128 v[108:111], v179 offset:17408
	ds_read_b128 v[150:153], v179 offset:25600
	s_waitcnt lgkmcnt(14)
	v_mfma_f32_16x16x32_bf16 v[192:195], v[112:115], v[48:51], v[192:195]
	v_mfma_f32_16x16x32_bf16 v[196:199], v[154:157], v[48:51], v[196:199]
	ds_read_b128 v[112:115], v179 offset:18432
	ds_read_b128 v[154:157], v179 offset:26624
	s_waitcnt lgkmcnt(14)
	v_mfma_f32_16x16x32_bf16 v[192:195], v[116:119], v[56:59], v[192:195]
	v_mfma_f32_16x16x32_bf16 v[196:199], v[158:161], v[56:59], v[196:199]
	ds_read_b128 v[116:119], v179 offset:19456
	ds_read_b128 v[158:161], v179 offset:27648
	s_waitcnt lgkmcnt(14)
	v_mfma_f32_16x16x32_bf16 v[192:195], v[120:123], v[72:75], v[192:195]
	v_mfma_f32_16x16x32_bf16 v[196:199], v[162:165], v[72:75], v[196:199]
	ds_read_b128 v[120:123], v179 offset:20480
	ds_read_b128 v[162:165], v179 offset:28672
	s_waitcnt lgkmcnt(14)
	v_mfma_f32_16x16x32_bf16 v[192:195], v[124:127], v[80:83], v[192:195]
	v_mfma_f32_16x16x32_bf16 v[196:199], v[166:169], v[80:83], v[196:199]
	ds_read_b128 v[124:127], v179 offset:21504
	ds_read_b128 v[166:169], v179 offset:29696
	s_waitcnt lgkmcnt(14)
	v_mfma_f32_16x16x32_bf16 v[192:195], v[128:131], v[88:91], v[192:195]
	v_mfma_f32_16x16x32_bf16 v[196:199], v[170:173], v[88:91], v[196:199]
	ds_read_b128 v[128:131], v179 offset:22528
	ds_read_b128 v[170:173], v179 offset:30720
	s_waitcnt lgkmcnt(14)
	v_mfma_f32_16x16x32_bf16 v[192:195], v[132:135], v[96:99], v[192:195]
	v_mfma_f32_16x16x32_bf16 v[196:199], v[174:177], v[96:99], v[196:199]
	ds_read_b128 v[132:135], v179 offset:23552
	ds_read_b128 v[174:177], v179 offset:31744
	v_mul_f32_e32 v206, v191, v206
	v_mul_f32_e32 v207, v191, v207
	v_mul_f32_e32 v208, v191, v208
	v_mul_f32_e32 v209, v191, v209
	v_cvt_pk_bf16_f32 v206, v206, v207
	v_cvt_pk_bf16_f32 v207, v208, v209
	global_store_dwordx2 v[184:185], v[206:207], off offset:192
	v_mul_f32_e32 v210, v191, v210
	v_mul_f32_e32 v211, v191, v211
	v_mul_f32_e32 v212, v191, v212
	v_mul_f32_e32 v213, v191, v213
	v_cvt_pk_bf16_f32 v210, v210, v211
	v_cvt_pk_bf16_f32 v211, v212, v213
	global_store_dwordx2 v[184:185], v[210:211], off offset:224
	s_waitcnt vmcnt(10)
	s_barrier
	s_waitcnt lgkmcnt(14)
	v_mfma_f32_16x16x32_bf16 v[206:209], v[104:107], v[32:35], 0
	v_mfma_f32_16x16x32_bf16 v[210:213], v[146:149], v[32:35], 0
	ds_read_b128 v[104:107], v179 offset:32768
	ds_read_b128 v[146:149], v179 offset:40960
	s_waitcnt lgkmcnt(14)
	v_mfma_f32_16x16x32_bf16 v[206:209], v[108:111], v[40:43], v[206:209]
	v_mfma_f32_16x16x32_bf16 v[210:213], v[150:153], v[40:43], v[210:213]
	ds_read_b128 v[108:111], v179 offset:33792
	ds_read_b128 v[150:153], v179 offset:41984
	s_waitcnt lgkmcnt(14)
	v_mfma_f32_16x16x32_bf16 v[206:209], v[112:115], v[48:51], v[206:209]
	v_mfma_f32_16x16x32_bf16 v[210:213], v[154:157], v[48:51], v[210:213]
	ds_read_b128 v[112:115], v179 offset:34816
	ds_read_b128 v[154:157], v179 offset:43008
	s_waitcnt lgkmcnt(14)
	v_mfma_f32_16x16x32_bf16 v[206:209], v[116:119], v[56:59], v[206:209]
	v_mfma_f32_16x16x32_bf16 v[210:213], v[158:161], v[56:59], v[210:213]
	ds_read_b128 v[116:119], v179 offset:35840
	ds_read_b128 v[158:161], v179 offset:44032
	s_waitcnt lgkmcnt(14)
	v_mfma_f32_16x16x32_bf16 v[206:209], v[120:123], v[72:75], v[206:209]
	v_mfma_f32_16x16x32_bf16 v[210:213], v[162:165], v[72:75], v[210:213]
	ds_read_b128 v[120:123], v179 offset:36864
	ds_read_b128 v[162:165], v179 offset:45056
	s_waitcnt lgkmcnt(14)
	v_mfma_f32_16x16x32_bf16 v[206:209], v[124:127], v[80:83], v[206:209]
	v_mfma_f32_16x16x32_bf16 v[210:213], v[166:169], v[80:83], v[210:213]
	ds_read_b128 v[124:127], v179 offset:37888
	ds_read_b128 v[166:169], v179 offset:46080
	s_waitcnt lgkmcnt(14)
	v_mfma_f32_16x16x32_bf16 v[206:209], v[128:131], v[88:91], v[206:209]
	v_mfma_f32_16x16x32_bf16 v[210:213], v[170:173], v[88:91], v[210:213]
	ds_read_b128 v[128:131], v179 offset:38912
	ds_read_b128 v[170:173], v179 offset:47104
	s_waitcnt lgkmcnt(14)
	v_mfma_f32_16x16x32_bf16 v[206:209], v[132:135], v[96:99], v[206:209]
	v_mfma_f32_16x16x32_bf16 v[210:213], v[174:177], v[96:99], v[210:213]
	ds_read_b128 v[132:135], v179 offset:39936
	ds_read_b128 v[174:177], v179 offset:48128
	v_mul_f32_e32 v192, v191, v192
	v_mul_f32_e32 v193, v191, v193
	v_mul_f32_e32 v194, v191, v194
	v_mul_f32_e32 v195, v191, v195
	v_cvt_pk_bf16_f32 v192, v192, v193
	v_cvt_pk_bf16_f32 v193, v194, v195
	global_store_dwordx2 v[184:185], v[192:193], off offset:256
	v_mul_f32_e32 v196, v191, v196
	v_mul_f32_e32 v197, v191, v197
	v_mul_f32_e32 v198, v191, v198
	v_mul_f32_e32 v199, v191, v199
	v_cvt_pk_bf16_f32 v196, v196, v197
	v_cvt_pk_bf16_f32 v197, v198, v199
	global_store_dwordx2 v[184:185], v[196:197], off offset:288
	s_waitcnt vmcnt(10)
	s_barrier
; __device__ __forceinline__ unsigned cvt_pk_bf16(float lo, float hi) { unsigned r; asm volatile("v_cvt_pk_bf16_f32 %0, %1, %2" : "=v"(r) : "v"(lo), "v"(hi)); return r; }
; __device__ __forceinline__ f32x4 mfma16(bf16x8 a, bf16x8 b, f32x4 c) { return __builtin_amdgcn_mfma_f32_16x16x32_bf16(a, b, c, 0, 0, 0); }
; __device__ __forceinline__ void mem_task(bf16_t* zb, const bf16_t* kvm_b, const bf16_t* vmt_b, int hm, int t0, int lane, bool do_store) {
;     ...
; #pragma unroll
;     for (int dt = 0; dt < 16; ++dt) {
;         if (dt + 2 < 16) { const bf16_t* vp = vbase + (size_t)((dt + 2) * 16) * 256;
; #pragma unroll
;             for (int kp = 0; kp < 8; ++kp) vfr[(dt + 2) % 3][kp] = *(const bf16x8*)(vp + kp * 32); }
;         f32x4 acc = zero4;
;         __builtin_amdgcn_s_setprio(1);
; #pragma unroll
;         for (int kp = 0; kp < 8; ++kp) acc = mfma16(vfr[dt % 3][kp], pf[kp], acc);
;         __builtin_amdgcn_s_setprio(0);
;         u32x2 w; w.x = cvt_pk_bf16(acc[0] * il, acc[1] * il); w.y = cvt_pk_bf16(acc[2] * il, acc[3] * il); if (do_store || acc[0] == 12345.678f) *(u32x2*)(qp + dt * 16 + 4 * fq) = w; }
; __global__ void __launch_bounds__(512, 2) mega(Args a) {
;     ...
;             for (int prep_ = 0; prep_ < PROBE_C2; ++prep_) for (int it = gw; it < (SEQ / 16) * 4; it += NGW) { const int hm = it & 3, t0 = (it >> 2) * 16;
;                 mem_task(ZMAIN, KVM + (size_t)b * 256 * 2048, VMT + (size_t)b * 4 * 256 * 256, hm, t0, lane, prep_ == PROBE_C2 - 1); }
	s_waitcnt lgkmcnt(14)
	v_mfma_f32_16x16x32_bf16 v[192:195], v[104:107], v[32:35], 0
	v_mfma_f32_16x16x32_bf16 v[196:199], v[146:149], v[32:35], 0
	ds_read_b128 v[104:107], v179 offset:49152
	ds_read_b128 v[146:149], v179 offset:57344
	s_waitcnt lgkmcnt(14)
	v_mfma_f32_16x16x32_bf16 v[192:195], v[108:111], v[40:43], v[192:195]
	v_mfma_f32_16x16x32_bf16 v[196:199], v[150:153], v[40:43], v[196:199]
	ds_read_b128 v[108:111], v179 offset:50176
	ds_read_b128 v[150:153], v179 offset:58368
	s_waitcnt lgkmcnt(14)
	v_mfma_f32_16x16x32_bf16 v[192:195], v[112:115], v[48:51], v[192:195]
	v_mfma_f32_16x16x32_bf16 v[196:199], v[154:157], v[48:51], v[196:199]
	ds_read_b128 v[112:115], v179 offset:51200
	ds_read_b128 v[154:157], v179 offset:59392
	s_waitcnt lgkmcnt(14)
	v_mfma_f32_16x16x32_bf16 v[192:195], v[116:119], v[56:59], v[192:195]
	v_mfma_f32_16x16x32_bf16 v[196:199], v[158:161], v[56:59], v[196:199]
	ds_read_b128 v[116:119], v179 offset:52224
	ds_read_b128 v[158:161], v179 offset:60416
	s_waitcnt lgkmcnt(14)
	v_mfma_f32_16x16x32_bf16 v[192:195], v[120:123], v[72:75], v[192:195]
	v_mfma_f32_16x16x32_bf16 v[196:199], v[162:165], v[72:75], v[196:199]
	ds_read_b128 v[120:123], v179 offset:53248
	ds_read_b128 v[162:165], v179 offset:61440
	s_waitcnt lgkmcnt(14)
	v_mfma_f32_16x16x32_bf16 v[192:195], v[124:127], v[80:83], v[192:195]
	v_mfma_f32_16x16x32_bf16 v[196:199], v[166:169], v[80:83], v[196:199]
	ds_read_b128 v[124:127], v179 offset:54272
	ds_read_b128 v[166:169], v179 offset:62464
	s_waitcnt lgkmcnt(14)
	v_mfma_f32_16x16x32_bf16 v[192:195], v[128:131], v[88:91], v[192:195]
	v_mfma_f32_16x16x32_bf16 v[196:199], v[170:173], v[88:91], v[196:199]
	ds_read_b128 v[128:131], v179 offset:55296
	ds_read_b128 v[170:173], v179 offset:63488
	s_waitcnt lgkmcnt(14)
	v_mfma_f32_16x16x32_bf16 v[192:195], v[132:135], v[96:99], v[192:195]
	v_mfma_f32_16x16x32_bf16 v[196:199], v[174:177], v[96:99], v[196:199]
	ds_read_b128 v[132:135], v179 offset:56320
	ds_read_b128 v[174:177], v179 offset:64512
	v_mul_f32_e32 v206, v191, v206
	v_mul_f32_e32 v207, v191, v207
	v_mul_f32_e32 v208, v191, v208
	v_mul_f32_e32 v209, v191, v209
	v_cvt_pk_bf16_f32 v206, v206, v207
	v_cvt_pk_bf16_f32 v207, v208, v209
	global_store_dwordx2 v[184:185], v[206:207], off offset:320
	v_mul_f32_e32 v210, v191, v210
	v_mul_f32_e32 v211, v191, v211
	v_mul_f32_e32 v212, v191, v212
	v_mul_f32_e32 v213, v191, v213
	v_cvt_pk_bf16_f32 v210, v210, v211
	v_cvt_pk_bf16_f32 v211, v212, v213
	global_store_dwordx2 v[184:185], v[210:211], off offset:352
	s_waitcnt lgkmcnt(14)
	v_mfma_f32_16x16x32_bf16 v[206:209], v[104:107], v[32:35], 0
	v_mfma_f32_16x16x32_bf16 v[210:213], v[146:149], v[32:35], 0
	s_waitcnt lgkmcnt(12)
	v_mfma_f32_16x16x32_bf16 v[206:209], v[108:111], v[40:43], v[206:209]
	v_mfma_f32_16x16x32_bf16 v[210:213], v[150:153], v[40:43], v[210:213]
	s_waitcnt lgkmcnt(10)
	v_mfma_f32_16x16x32_bf16 v[206:209], v[112:115], v[48:51], v[206:209]
	v_mfma_f32_16x16x32_bf16 v[210:213], v[154:157], v[48:51], v[210:213]
	s_waitcnt lgkmcnt(8)
	v_mfma_f32_16x16x32_bf16 v[206:209], v[116:119], v[56:59], v[206:209]
	v_mfma_f32_16x16x32_bf16 v[210:213], v[158:161], v[56:59], v[210:213]
	s_waitcnt lgkmcnt(6)
	v_mfma_f32_16x16x32_bf16 v[206:209], v[120:123], v[72:75], v[206:209]
	v_mfma_f32_16x16x32_bf16 v[210:213], v[162:165], v[72:75], v[210:213]
	s_waitcnt lgkmcnt(4)
	v_mfma_f32_16x16x32_bf16 v[206:209], v[124:127], v[80:83], v[206:209]
	v_mfma_f32_16x16x32_bf16 v[210:213], v[166:169], v[80:83], v[210:213]
	s_waitcnt lgkmcnt(2)
	v_mfma_f32_16x16x32_bf16 v[206:209], v[128:131], v[88:91], v[206:209]
	v_mfma_f32_16x16x32_bf16 v[210:213], v[170:173], v[88:91], v[210:213]
	s_waitcnt lgkmcnt(0)
	v_mfma_f32_16x16x32_bf16 v[206:209], v[132:135], v[96:99], v[206:209]
	v_mfma_f32_16x16x32_bf16 v[210:213], v[174:177], v[96:99], v[210:213]
	v_mul_f32_e32 v192, v191, v192
	v_mul_f32_e32 v193, v191, v193
	v_mul_f32_e32 v194, v191, v194
	v_mul_f32_e32 v195, v191, v195
	v_cvt_pk_bf16_f32 v192, v192, v193
	v_cvt_pk_bf16_f32 v193, v194, v195
	global_store_dwordx2 v[184:185], v[192:193], off offset:384
	v_mul_f32_e32 v196, v191, v196
	v_mul_f32_e32 v197, v191, v197
	v_mul_f32_e32 v198, v191, v198
	v_mul_f32_e32 v199, v191, v199
	v_cvt_pk_bf16_f32 v196, v196, v197
	v_cvt_pk_bf16_f32 v197, v198, v199
	global_store_dwordx2 v[184:185], v[196:197], off offset:416
	s_nop 7
	s_nop 7
	v_mul_f32_e32 v206, v191, v206
	v_mul_f32_e32 v207, v191, v207
	v_mul_f32_e32 v208, v191, v208
	v_mul_f32_e32 v209, v191, v209
	v_cvt_pk_bf16_f32 v206, v206, v207
	v_cvt_pk_bf16_f32 v207, v208, v209
	global_store_dwordx2 v[184:185], v[206:207], off offset:448
	v_mul_f32_e32 v210, v191, v210
	v_mul_f32_e32 v211, v191, v211
	v_mul_f32_e32 v212, v191, v212
	v_mul_f32_e32 v213, v191, v213
	v_cvt_pk_bf16_f32 v210, v210, v211
	v_cvt_pk_bf16_f32 v211, v212, v213
	global_store_dwordx2 v[184:185], v[210:211], off offset:480
	s_add_i32 s5, s5, s64
	s_cmpk_gt_i32 s5, 0x7ff
	s_cbranch_scc0 .LBB0_366
